# final LayerNorm wave sums via DPP and permlane swaps instead of six serialized ds_bpermute round trips each
# speedup vs baseline: 1.0154x; 1.0154x over previous
.LBB0_3492:
	s_waitcnt vmcnt(4)
	v_mov_b32_e32 v30, v104
	v_mov_b32_e32 v31, v105
	v_mov_b32_e32 v32, v106
	v_mov_b32_e32 v33, v107
	v_mov_b32_e32 v34, v108
	v_mov_b32_e32 v35, v109
	v_mov_b32_e32 v36, v110
	v_mov_b32_e32 v37, v111
	v_add_u32_e32 v0, s96, v0
	v_lshl_add_u64 v[18:19], v[18:19], 0, s[2:3]
	global_load_dwordx4 v[104:107], v[18:19], off offset:-1024
	global_load_dwordx4 v[108:111], v[18:19], off
	v_mov_b32_e32 v38, v72
	v_mov_b32_e32 v39, v73
	v_mov_b32_e32 v40, v74
	v_mov_b32_e32 v41, v75
	v_mov_b32_e32 v42, v76
	v_mov_b32_e32 v43, v77
	v_mov_b32_e32 v44, v78
	v_mov_b32_e32 v45, v79
	v_cvt_f32_f16_sdwa v46, v30 dst_sel:DWORD dst_unused:UNUSED_PAD src0_sel:WORD_1
	v_cvt_f32_f16_e32 v48, v30
	v_cvt_f32_f16_sdwa v47, v31 dst_sel:DWORD dst_unused:UNUSED_PAD src0_sel:WORD_1
	v_cvt_f32_f16_e32 v49, v31
	v_cvt_f32_f16_sdwa v50, v32 dst_sel:DWORD dst_unused:UNUSED_PAD src0_sel:WORD_1
	v_cvt_f32_f16_e32 v52, v32
	v_cvt_f32_f16_sdwa v51, v33 dst_sel:DWORD dst_unused:UNUSED_PAD src0_sel:WORD_1
	v_cvt_f32_f16_e32 v53, v33
	v_cvt_f32_f16_sdwa v29, v34 dst_sel:DWORD dst_unused:UNUSED_PAD src0_sel:WORD_1
	v_cvt_f32_f16_e32 v55, v34
	v_cvt_f32_f16_sdwa v59, v35 dst_sel:DWORD dst_unused:UNUSED_PAD src0_sel:WORD_1
	v_cvt_f32_f16_e32 v61, v35
	v_cvt_f32_f16_sdwa v54, v36 dst_sel:DWORD dst_unused:UNUSED_PAD src0_sel:WORD_1
	v_cvt_f32_f16_e32 v56, v36
	v_cvt_f32_f16_sdwa v58, v37 dst_sel:DWORD dst_unused:UNUSED_PAD src0_sel:WORD_1
	v_cvt_f32_f16_e32 v60, v37
	v_pk_add_f32 v[46:47], v[48:49], v[46:47]
	v_pk_add_f32 v[48:49], v[52:53], v[50:51]
	v_add_f32_e32 v57, v55, v29
	v_add_f32_e32 v29, v46, v47
	v_pk_add_f32 v[46:47], v[48:49], v[48:49] op_sel_hi:[0,1]
	v_add_f32_e32 v55, v61, v59
	v_add_f32_e32 v59, 0, v29
	v_mov_b32_e32 v61, v47
	v_pk_add_f32 v[48:49], v[56:57], v[54:55]
	v_pk_add_f32 v[46:47], v[60:61], v[58:59]
	s_nop 0
	v_pk_add_f32 v[46:47], v[48:49], v[46:47]
	s_nop 0
	v_add_f32_e32 v29, v46, v47
	s_nop 1
	v_add_f32_dpp v29, v29, v29 quad_perm:[1,0,3,2] row_mask:0xf bank_mask:0xf
	s_nop 1
	v_add_f32_dpp v29, v29, v29 quad_perm:[2,3,0,1] row_mask:0xf bank_mask:0xf
	s_nop 1
	v_add_f32_dpp v29, v29, v29 row_half_mirror row_mask:0xf bank_mask:0xf
	s_nop 1
	v_add_f32_dpp v29, v29, v29 row_mirror row_mask:0xf bank_mask:0xf
	s_nop 0
	v_mov_b32_e32 v46, v29
	s_nop 1
	v_permlane16_swap_b32 v46, v29
	s_nop 0
	v_add_f32_e32 v29, v29, v46
	s_nop 0
	v_mov_b32_e32 v46, v29
	s_nop 1
	v_permlane32_swap_b32 v46, v29
	s_nop 0
	v_add_f32_e32 v29, v29, v46
	v_fma_mix_f32 v47, v29, s8, v30 op_sel:[0,0,1] op_sel_hi:[0,0,1]
	v_fma_mix_f32 v46, v29, s8, v30 op_sel_hi:[0,0,1]
	v_fma_mix_f32 v49, v29, s8, v31 op_sel:[0,0,1] op_sel_hi:[0,0,1]
	v_fma_mix_f32 v48, v29, s8, v31 op_sel_hi:[0,0,1]
	v_fma_mix_f32 v51, v29, s8, v32 op_sel:[0,0,1] op_sel_hi:[0,0,1]
	v_fma_mix_f32 v50, v29, s8, v32 op_sel_hi:[0,0,1]
	v_fma_mix_f32 v53, v29, s8, v33 op_sel:[0,0,1] op_sel_hi:[0,0,1]
	v_fma_mix_f32 v52, v29, s8, v33 op_sel_hi:[0,0,1]
	v_fma_mix_f32 v55, v29, s8, v34 op_sel:[0,0,1] op_sel_hi:[0,0,1]
	v_fma_mix_f32 v54, v29, s8, v34 op_sel_hi:[0,0,1]
	v_fma_mix_f32 v57, v29, s8, v35 op_sel:[0,0,1] op_sel_hi:[0,0,1]
	v_fma_mix_f32 v56, v29, s8, v35 op_sel_hi:[0,0,1]
	v_fma_mix_f32 v59, v29, s8, v37 op_sel:[0,0,1] op_sel_hi:[0,0,1]
	v_fma_mix_f32 v58, v29, s8, v37 op_sel_hi:[0,0,1]
	v_fma_mix_f32 v61, v29, s8, v36 op_sel:[0,0,1] op_sel_hi:[0,0,1]
	v_fma_mix_f32 v60, v29, s8, v36 op_sel_hi:[0,0,1]
	v_pk_mul_f32 v[30:31], v[48:49], v[48:49]
	v_pk_mul_f32 v[32:33], v[46:47], v[46:47]
	v_pk_mul_f32 v[34:35], v[52:53], v[52:53]
	v_pk_mul_f32 v[36:37], v[50:51], v[50:51]
	v_pk_mov_b32 v[66:67], v[32:33], v[30:31] op_sel:[1,0]
	v_mov_b32_e32 v33, v31
	v_pk_mov_b32 v[30:31], v[36:37], v[34:35] op_sel:[1,0]
	v_mov_b32_e32 v37, v35
	v_mul_f32_e32 v62, v54, v54
	v_mul_f32_e32 v64, v56, v56
	v_pk_add_f32 v[32:33], v[66:67], v[32:33]
	v_pk_add_f32 v[30:31], v[30:31], v[36:37]
	v_pk_fma_f32 v[34:35], v[54:55], v[54:55], v[62:63] op_sel_hi:[1,1,0]
	v_pk_fma_f32 v[62:63], v[56:57], v[56:57], v[64:65] op_sel_hi:[1,1,0]
	v_pk_add_f32 v[32:33], v[32:33], v[32:33] op_sel_hi:[0,1]
	v_pk_add_f32 v[30:31], v[30:31], v[30:31] op_sel_hi:[0,1]
	v_mul_f32_e32 v34, v60, v60
	v_mul_f32_e32 v62, v61, v61
	v_mul_f32_e32 v32, v58, v58
	v_mul_f32_e32 v30, v59, v59
	v_pk_add_f32 v[34:35], v[34:35], v[62:63]
	v_pk_add_f32 v[30:31], v[32:33], v[30:31]
	s_nop 0
	v_pk_add_f32 v[30:31], v[34:35], v[30:31]
	s_nop 0
	v_add_f32_e32 v29, v30, v31
	s_nop 1
	v_add_f32_dpp v29, v29, v29 quad_perm:[1,0,3,2] row_mask:0xf bank_mask:0xf
	s_nop 1
	v_add_f32_dpp v29, v29, v29 quad_perm:[2,3,0,1] row_mask:0xf bank_mask:0xf
	s_nop 1
	v_add_f32_dpp v29, v29, v29 row_half_mirror row_mask:0xf bank_mask:0xf
	s_nop 1
	v_add_f32_dpp v29, v29, v29 row_mirror row_mask:0xf bank_mask:0xf
	s_nop 0
	v_mov_b32_e32 v30, v29
	s_nop 1
	v_permlane16_swap_b32 v30, v29
	s_nop 0
	v_add_f32_e32 v29, v29, v30
	s_nop 0
	v_mov_b32_e32 v30, v29
	s_nop 1
	v_permlane32_swap_b32 v30, v29
	s_nop 0
	v_add_f32_e32 v29, v29, v30
	v_fmamk_f32 v29, v29, 0x3a800000, v1
	v_mul_f32_e32 v30, 0x4f800000, v29
	v_cmp_gt_f32_e32 vcc, s9, v29
	s_nop 1
	v_cndmask_b32_e32 v29, v29, v30, vcc
	v_sqrt_f32_e32 v30, v29
	s_nop 0
	v_add_u32_e32 v31, -1, v30
	v_add_u32_e32 v32, 1, v30
	v_fma_f32 v33, -v31, v30, v29
	v_fma_f32 v34, -v32, v30, v29
	v_cmp_ge_f32_e64 s[0:1], 0, v33
	s_nop 1
	v_cndmask_b32_e64 v30, v30, v31, s[0:1]
	v_cmp_lt_f32_e64 s[0:1], 0, v34
	s_nop 1
	v_cndmask_b32_e64 v30, v30, v32, s[0:1]
	v_mul_f32_e32 v31, 0x37800000, v30
	v_cndmask_b32_e32 v30, v30, v31, vcc
	v_cmp_class_f32_e32 vcc, v29, v28
	s_nop 1
	v_cndmask_b32_e32 v29, v30, v29, vcc
	v_div_scale_f32 v30, s[0:1], v29, v29, 1.0
	v_rcp_f32_e32 v32, v30
	v_div_scale_f32 v31, vcc, 1.0, v29, 1.0
	v_fma_f32 v33, -v30, v32, 1.0
	v_fmac_f32_e32 v32, v33, v32
	v_mul_f32_e32 v33, v31, v32
	v_fma_f32 v34, -v30, v33, v31
	v_fmac_f32_e32 v33, v34, v32
	v_fma_f32 v30, -v30, v33, v31
	v_div_fmas_f32 v30, v30, v32, v33
	v_div_fixup_f32 v62, v30, v29, 1.0
	v_pk_mul_f32 v[30:31], v[46:47], v[62:63] op_sel_hi:[1,0]
	v_pk_mul_f32 v[32:33], v[48:49], v[62:63] op_sel_hi:[1,0]
	v_pk_fma_f32 v[30:31], v[38:39], v[30:31], v[42:43]
	v_pk_fma_f32 v[32:33], v[40:41], v[32:33], v[44:45]
	global_store_dwordx4 v[20:21], v[30:33], off
	s_nop 1
	v_mov_b32_e32 v30, v80
	v_mov_b32_e32 v31, v81
	v_mov_b32_e32 v32, v82
	v_mov_b32_e32 v33, v83
	s_nop 0
	v_mov_b32_e32 v34, v84
	v_mov_b32_e32 v35, v85
	v_mov_b32_e32 v36, v86
	v_mov_b32_e32 v37, v87
	v_pk_mul_f32 v[38:39], v[52:53], v[62:63] op_sel_hi:[1,0]
	v_pk_mul_f32 v[40:41], v[50:51], v[62:63] op_sel_hi:[1,0]
	v_cmp_lt_i32_e32 vcc, s10, v0
	s_or_b64 s[6:7], vcc, s[6:7]
	v_pk_fma_f32 v[30:31], v[30:31], v[40:41], v[34:35]
	v_pk_fma_f32 v[32:33], v[32:33], v[38:39], v[36:37]
	global_store_dwordx4 v[20:21], v[30:33], off offset:16
	s_nop 1
	v_mov_b32_e32 v30, v88
	v_mov_b32_e32 v31, v89
	v_mov_b32_e32 v32, v90
	v_mov_b32_e32 v33, v91
	s_nop 0
	v_mov_b32_e32 v34, v92
	v_mov_b32_e32 v35, v93
	v_mov_b32_e32 v36, v94
	v_mov_b32_e32 v37, v95
	v_pk_mul_f32 v[38:39], v[56:57], v[62:63] op_sel_hi:[1,0]
	v_pk_mul_f32 v[40:41], v[54:55], v[62:63] op_sel_hi:[1,0]
	v_pk_fma_f32 v[32:33], v[32:33], v[38:39], v[36:37]
	v_pk_fma_f32 v[30:31], v[30:31], v[40:41], v[34:35]
	global_store_dwordx4 v[20:21], v[30:33], off offset:2048
	s_nop 1
	v_mov_b32_e32 v30, v96
	v_mov_b32_e32 v31, v97
	v_mov_b32_e32 v32, v98
	v_mov_b32_e32 v33, v99
	s_nop 0
	v_mov_b32_e32 v34, v100
	v_mov_b32_e32 v35, v101
	v_mov_b32_e32 v36, v102
	v_mov_b32_e32 v37, v103
	v_pk_mul_f32 v[38:39], v[58:59], v[62:63] op_sel_hi:[1,0]
	v_pk_mul_f32 v[40:41], v[60:61], v[62:63] op_sel_hi:[1,0]
	v_pk_fma_f32 v[32:33], v[32:33], v[38:39], v[36:37]
	v_pk_fma_f32 v[30:31], v[30:31], v[40:41], v[34:35]
	global_store_dwordx4 v[20:21], v[30:33], off offset:2064
	v_lshl_add_u64 v[20:21], v[20:21], 0, s[4:5]
	s_andn2_b64 exec, exec, s[6:7]
	s_cbranch_execnz .LBB0_3492
